# near-path softmax now waits for the K-tile DMA pieces before the softmax (vmcnt(8)) so the next tile's LDS reads never race the DMA landing
# baseline (speedup 1.0000x reference)
.Lattn_near_p:
	s_waitcnt vmcnt(8)
	v_subrev_u32_e32 v188, 64, v177
	v_xor_b32_e32 v232, 32, v179
	v_lshlrev_b32_e32 v232, 2, v232
	v_max3_f32 v231, v98, v99, v100
	v_max3_f32 v231, v231, v101, v102
	v_max3_f32 v231, v231, v103, v104
	v_max3_f32 v231, v231, v105, v106
	v_max3_f32 v231, v231, v107, v108
	v_max3_f32 v231, v231, v109, v110
	v_max3_f32 v231, v231, v111, v112
	v_max3_f32 v231, v231, v113, v114
	v_max3_f32 v231, v231, v115, v116
	v_max3_f32 v231, v231, v117, v118
	v_max3_f32 v231, v231, v119, v120
	v_max3_f32 v231, v231, v121, v122
	v_max3_f32 v231, v231, v123, v124
	v_max3_f32 v231, v231, v125, v126
	v_max3_f32 v231, v231, v127, v128
	v_max_f32_e32 v231, v231, v129
	s_waitcnt lgkmcnt(0)
	v_fma_f32 v231, v231, v249, v190
	ds_bpermute_b32 v233, v232, v231
	v_max3_f32 v234, v66, v67, v68
	v_max3_f32 v234, v234, v69, v70
	v_max3_f32 v234, v234, v71, v72
	v_max3_f32 v234, v234, v73, v74
	v_max3_f32 v234, v234, v75, v76
	v_max3_f32 v234, v234, v77, v78
	v_max3_f32 v234, v234, v79, v80
	v_max3_f32 v234, v234, v81, v82
	v_max3_f32 v234, v234, v83, v84
	v_max3_f32 v234, v234, v85, v86
	v_max3_f32 v234, v234, v87, v88
	v_max3_f32 v234, v234, v89, v90
	v_max3_f32 v234, v234, v91, v92
	v_max3_f32 v234, v234, v93, v94
	v_max3_f32 v234, v234, v95, v96
	v_max_f32_e32 v234, v234, v97
	v_fma_f32 v234, v234, v249, v190
	ds_bpermute_b32 v235, v232, v234
	s_waitcnt lgkmcnt(1)
	v_max3_f32 v236, v199, v231, v233
	v_sub_f32_e32 v226, v199, v236
	v_sub_f32_e32 v238, v190, v236
	v_exp_f32_e32 v226, v226
	v_pk_fma_f32 v[98:99], v[98:99], v[248:249], v[238:239] op_sel:[0,1,0] op_sel_hi:[1,1,0]
	v_pk_fma_f32 v[100:101], v[100:101], v[248:249], v[238:239] op_sel:[0,1,0] op_sel_hi:[1,1,0]
	v_pk_fma_f32 v[102:103], v[102:103], v[248:249], v[238:239] op_sel:[0,1,0] op_sel_hi:[1,1,0]
	v_pk_fma_f32 v[104:105], v[104:105], v[248:249], v[238:239] op_sel:[0,1,0] op_sel_hi:[1,1,0]
	v_pk_fma_f32 v[106:107], v[106:107], v[248:249], v[238:239] op_sel:[0,1,0] op_sel_hi:[1,1,0]
	v_pk_fma_f32 v[108:109], v[108:109], v[248:249], v[238:239] op_sel:[0,1,0] op_sel_hi:[1,1,0]
	v_pk_fma_f32 v[110:111], v[110:111], v[248:249], v[238:239] op_sel:[0,1,0] op_sel_hi:[1,1,0]
	v_pk_fma_f32 v[112:113], v[112:113], v[248:249], v[238:239] op_sel:[0,1,0] op_sel_hi:[1,1,0]
	v_pk_fma_f32 v[114:115], v[114:115], v[248:249], v[238:239] op_sel:[0,1,0] op_sel_hi:[1,1,0]
	v_pk_fma_f32 v[116:117], v[116:117], v[248:249], v[238:239] op_sel:[0,1,0] op_sel_hi:[1,1,0]
	v_pk_fma_f32 v[118:119], v[118:119], v[248:249], v[238:239] op_sel:[0,1,0] op_sel_hi:[1,1,0]
	v_pk_fma_f32 v[120:121], v[120:121], v[248:249], v[238:239] op_sel:[0,1,0] op_sel_hi:[1,1,0]
	v_pk_fma_f32 v[122:123], v[122:123], v[248:249], v[238:239] op_sel:[0,1,0] op_sel_hi:[1,1,0]
	v_pk_fma_f32 v[124:125], v[124:125], v[248:249], v[238:239] op_sel:[0,1,0] op_sel_hi:[1,1,0]
	v_pk_fma_f32 v[126:127], v[126:127], v[248:249], v[238:239] op_sel:[0,1,0] op_sel_hi:[1,1,0]
	v_pk_fma_f32 v[128:129], v[128:129], v[248:249], v[238:239] op_sel:[0,1,0] op_sel_hi:[1,1,0]
	v_exp_f32_e32 v98, v98
	v_exp_f32_e32 v99, v99
	v_exp_f32_e32 v100, v100
	v_exp_f32_e32 v101, v101
	v_exp_f32_e32 v102, v102
	v_exp_f32_e32 v103, v103
	v_exp_f32_e32 v104, v104
	v_exp_f32_e32 v105, v105
	v_exp_f32_e32 v106, v106
	v_exp_f32_e32 v107, v107
	v_exp_f32_e32 v108, v108
	v_exp_f32_e32 v109, v109
	v_exp_f32_e32 v110, v110
	v_exp_f32_e32 v111, v111
	v_exp_f32_e32 v112, v112
	v_exp_f32_e32 v113, v113
	v_exp_f32_e32 v114, v114
	v_exp_f32_e32 v115, v115
	v_exp_f32_e32 v116, v116
	v_exp_f32_e32 v117, v117
	v_exp_f32_e32 v118, v118
	v_exp_f32_e32 v119, v119
	v_exp_f32_e32 v120, v120
	v_exp_f32_e32 v121, v121
	v_exp_f32_e32 v122, v122
	v_exp_f32_e32 v123, v123
	v_exp_f32_e32 v124, v124
	v_exp_f32_e32 v125, v125
	v_exp_f32_e32 v126, v126
	v_exp_f32_e32 v127, v127
	v_exp_f32_e32 v128, v128
	v_exp_f32_e32 v129, v129
	s_waitcnt lgkmcnt(0)
	v_max3_f32 v218, v189, v234, v235
	v_sub_f32_e32 v228, v189, v218
	v_sub_f32_e32 v240, v190, v218
	v_exp_f32_e32 v228, v228
	v_pk_fma_f32 v[66:67], v[66:67], v[248:249], v[240:241] op_sel:[0,1,0] op_sel_hi:[1,1,0]
	v_pk_fma_f32 v[68:69], v[68:69], v[248:249], v[240:241] op_sel:[0,1,0] op_sel_hi:[1,1,0]
	v_pk_fma_f32 v[70:71], v[70:71], v[248:249], v[240:241] op_sel:[0,1,0] op_sel_hi:[1,1,0]
	v_pk_fma_f32 v[72:73], v[72:73], v[248:249], v[240:241] op_sel:[0,1,0] op_sel_hi:[1,1,0]
	v_pk_fma_f32 v[74:75], v[74:75], v[248:249], v[240:241] op_sel:[0,1,0] op_sel_hi:[1,1,0]
	v_pk_fma_f32 v[76:77], v[76:77], v[248:249], v[240:241] op_sel:[0,1,0] op_sel_hi:[1,1,0]
	v_pk_fma_f32 v[78:79], v[78:79], v[248:249], v[240:241] op_sel:[0,1,0] op_sel_hi:[1,1,0]
	v_pk_fma_f32 v[80:81], v[80:81], v[248:249], v[240:241] op_sel:[0,1,0] op_sel_hi:[1,1,0]
	v_pk_fma_f32 v[82:83], v[82:83], v[248:249], v[240:241] op_sel:[0,1,0] op_sel_hi:[1,1,0]
	v_pk_fma_f32 v[84:85], v[84:85], v[248:249], v[240:241] op_sel:[0,1,0] op_sel_hi:[1,1,0]
	v_pk_fma_f32 v[86:87], v[86:87], v[248:249], v[240:241] op_sel:[0,1,0] op_sel_hi:[1,1,0]
	v_pk_fma_f32 v[88:89], v[88:89], v[248:249], v[240:241] op_sel:[0,1,0] op_sel_hi:[1,1,0]
	v_pk_fma_f32 v[90:91], v[90:91], v[248:249], v[240:241] op_sel:[0,1,0] op_sel_hi:[1,1,0]
	v_pk_fma_f32 v[92:93], v[92:93], v[248:249], v[240:241] op_sel:[0,1,0] op_sel_hi:[1,1,0]
	v_pk_fma_f32 v[94:95], v[94:95], v[248:249], v[240:241] op_sel:[0,1,0] op_sel_hi:[1,1,0]
	v_pk_fma_f32 v[96:97], v[96:97], v[248:249], v[240:241] op_sel:[0,1,0] op_sel_hi:[1,1,0]
	v_exp_f32_e32 v66, v66
	v_exp_f32_e32 v67, v67
	v_exp_f32_e32 v68, v68
	v_exp_f32_e32 v69, v69
	v_exp_f32_e32 v70, v70
	v_exp_f32_e32 v71, v71
	v_exp_f32_e32 v72, v72
	v_exp_f32_e32 v73, v73
	v_exp_f32_e32 v74, v74
	v_exp_f32_e32 v75, v75
	v_exp_f32_e32 v76, v76
	v_exp_f32_e32 v77, v77
	v_exp_f32_e32 v78, v78
	v_exp_f32_e32 v79, v79
	v_exp_f32_e32 v80, v80
	v_exp_f32_e32 v81, v81
	v_exp_f32_e32 v82, v82
	v_exp_f32_e32 v83, v83
	v_exp_f32_e32 v84, v84
	v_exp_f32_e32 v85, v85
	v_exp_f32_e32 v86, v86
	v_exp_f32_e32 v87, v87
	v_exp_f32_e32 v88, v88
	v_exp_f32_e32 v89, v89
	v_exp_f32_e32 v90, v90
	v_exp_f32_e32 v91, v91
	v_exp_f32_e32 v92, v92
	v_exp_f32_e32 v93, v93
	v_exp_f32_e32 v94, v94
	v_exp_f32_e32 v95, v95
	v_exp_f32_e32 v96, v96
	v_exp_f32_e32 v97, v97
	v_pk_add_f32 v[212:213], v[98:99], v[100:101]
	v_pk_add_f32 v[214:215], v[102:103], v[104:105]
	v_pk_add_f32 v[212:213], v[212:213], v[106:107]
	v_pk_add_f32 v[214:215], v[214:215], v[108:109]
	v_pk_add_f32 v[212:213], v[212:213], v[110:111]
	v_pk_add_f32 v[214:215], v[214:215], v[112:113]
	v_pk_add_f32 v[212:213], v[212:213], v[114:115]
	v_pk_add_f32 v[214:215], v[214:215], v[116:117]
	v_pk_add_f32 v[212:213], v[212:213], v[118:119]
	v_pk_add_f32 v[214:215], v[214:215], v[120:121]
	v_pk_add_f32 v[212:213], v[212:213], v[122:123]
	v_pk_add_f32 v[214:215], v[214:215], v[124:125]
	v_pk_add_f32 v[212:213], v[212:213], v[126:127]
	v_pk_add_f32 v[214:215], v[214:215], v[128:129]
	v_pk_add_f32 v[212:213], v[212:213], v[214:215]
	v_add_f32_e32 v210, v212, v213
	ds_bpermute_b32 v211, v232, v210
	v_pk_add_f32 v[220:221], v[66:67], v[68:69]
	v_pk_add_f32 v[222:223], v[70:71], v[72:73]
	v_pk_add_f32 v[220:221], v[220:221], v[74:75]
	v_pk_add_f32 v[222:223], v[222:223], v[76:77]
	v_pk_add_f32 v[220:221], v[220:221], v[78:79]
	v_pk_add_f32 v[222:223], v[222:223], v[80:81]
	v_pk_add_f32 v[220:221], v[220:221], v[82:83]
	v_pk_add_f32 v[222:223], v[222:223], v[84:85]
	v_pk_add_f32 v[220:221], v[220:221], v[86:87]
	v_pk_add_f32 v[222:223], v[222:223], v[88:89]
	v_pk_add_f32 v[220:221], v[220:221], v[90:91]
	v_pk_add_f32 v[222:223], v[222:223], v[92:93]
	v_pk_add_f32 v[220:221], v[220:221], v[94:95]
	v_pk_add_f32 v[222:223], v[222:223], v[96:97]
	v_pk_add_f32 v[220:221], v[220:221], v[222:223]
	v_add_f32_e32 v224, v220, v221
	ds_bpermute_b32 v225, v232, v224
	v_cmp_neq_f32_e32 vcc, 1.0, v226
	s_cbranch_vccz .Lattn_near_p_sa
	v_pk_mul_f32 v[64:65], v[64:65], v[226:227] op_sel_hi:[1,0]
	v_pk_mul_f32 v[62:63], v[62:63], v[226:227] op_sel_hi:[1,0]
	v_pk_mul_f32 v[60:61], v[60:61], v[226:227] op_sel_hi:[1,0]
	v_pk_mul_f32 v[58:59], v[58:59], v[226:227] op_sel_hi:[1,0]
	v_pk_mul_f32 v[56:57], v[56:57], v[226:227] op_sel_hi:[1,0]
	v_pk_mul_f32 v[54:55], v[54:55], v[226:227] op_sel_hi:[1,0]
	v_pk_mul_f32 v[52:53], v[52:53], v[226:227] op_sel_hi:[1,0]
	v_pk_mul_f32 v[50:51], v[50:51], v[226:227] op_sel_hi:[1,0]
	v_pk_mul_f32 v[48:49], v[48:49], v[226:227] op_sel_hi:[1,0]
	v_pk_mul_f32 v[46:47], v[46:47], v[226:227] op_sel_hi:[1,0]
	v_pk_mul_f32 v[44:45], v[44:45], v[226:227] op_sel_hi:[1,0]
	v_pk_mul_f32 v[42:43], v[42:43], v[226:227] op_sel_hi:[1,0]
	v_pk_mul_f32 v[40:41], v[40:41], v[226:227] op_sel_hi:[1,0]
	v_pk_mul_f32 v[38:39], v[38:39], v[226:227] op_sel_hi:[1,0]
	v_pk_mul_f32 v[36:37], v[36:37], v[226:227] op_sel_hi:[1,0]
	v_pk_mul_f32 v[34:35], v[34:35], v[226:227] op_sel_hi:[1,0]
